# attention loop: unconditional tile loads/LDS writes (tail reads stay inside workspace, images never consumed), loop-control scalar code removed, 64-bit address adds folded, back edge rotated
# speedup vs baseline: 1.0067x; 1.0067x over previous
; DI int lane_id() { int l; asm volatile("v_mbcnt_lo_u32_b32 %0, -1, 0\n\tv_mbcnt_hi_u32_b32 %0, -1, %0" : "=v"(l)); return l; }
; DI void attn_phase(LAS unsigned char* lds, const int wid, const bf16_t* Q, const bf16_t* Kn, const bf16_t* Kr, const bf16_t* Vt, bf16_t* O, int G, int c) {
;     const int lane = lane_id(), tid = wid * 64 + lane, r16 = lane & 15, qd = lane >> 4;
;     for (int it = 0;; ++it) {
;         const long L = (long)it * G + c; if (L >= 2048) break;
;         const int xcd = (int)(L & 7), idx = (int)(L >> 3), bh = (idx >> 5) * 8 + xcd, qb = idx & 31, b = bh >> 3, h = bh & 7;
;         const size_t tok0 = (size_t)b * SEQ;
;         const int q0 = qb * 256 + wid * 32;
;         bf16x8 qf[2][3];
; #pragma unroll
;         for (int qt = 0; qt < 2; ++qt) { const bf16_t* qp = Q + (tok0 + q0 + 16 * qt + r16) * 768 + h * 96 + 8 * qd;
; #pragma unroll
;           for (int ks = 0; ks < 3; ++ks) qf[qt][ks] = *(const bf16x8*)(qp + 32 * ks); }
;         f32x4 oacc[4][2], sa[4][2], sb[4][2];
;         f32x4 negm0 = {0.f, 0.f, 0.f, 0.f}, negm1 = {0.f, 0.f, 0.f, 0.f};
; #pragma unroll
;         for (int t4 = 0; t4 < 4; ++t4) { oacc[t4][0] = (f32x4){0.f, 0.f, 0.f, 0.f}; oacc[t4][1] = (f32x4){0.f, 0.f, 0.f, 0.f}; }
;         float l0 = 0.f, l1 = 0.f;
;         const int skey = tid >> 3, sch = tid & 7;
;         const int rkey = (tid & 255) >> 2, rch = tid & 3;
;         const bf16_t* gkn = Kn + (tok0 + skey) * 512 + h * 64 + sch * 8;
;         const bf16_t* gkr = Kr + (tok0 + rkey) * 32 + rch * 8;
;         const bf16_t* gvt = Vt + (size_t)(h * 64 + skey) * T + tok0 + sch * 8;
;         const unsigned lkn = skey * KS_STRIDE + sch * 16, lkr = rkey * KS_STRIDE + 128 + rch * 16, lvt = VOFF + skey * VS_STRIDE + (sch >> 2) * 64 + ((sch & 1) * 4 + ((sch >> 1) & 1)) * 8;
.LBB0_856:
	s_mov_b64 s[6:7], s[0:1]
	s_mov_b64 s[8:9], s[0:1]
	s_load_dwordx2 s[6:7], s[6:7], 0xf8
	s_mov_b64 s[10:11], s[0:1]
	s_load_dwordx2 s[8:9], s[8:9], 0xf8
	s_load_dwordx2 s[14:15], s[10:11], 0xf8
	s_mov_b64 s[10:11], s[0:1]
	s_load_dwordx2 s[28:29], s[10:11], 0xf8
	s_mov_b64 s[10:11], s[0:1]
	s_load_dwordx2 s[16:17], s[10:11], 0xf8
	v_mbcnt_lo_u32_b32 v1, -1, 0
	v_mbcnt_hi_u32_b32 v1, -1, v1
	v_mov_b32_e32 v0, 0
	v_ashrrev_i32_e32 v9, 4, v1
	v_lshlrev_b32_e32 v2, 3, v9
	v_ashrrev_i32_e32 v3, 31, v2
	s_waitcnt lgkmcnt(0)
	v_lshl_add_u64 v[2:3], v[2:3], 1, s[6:7]
	s_mov_b64 s[6:7], 0x26cc0000
	v_lshlrev_b32_e32 v4, 4, v1
	v_add_u32_e32 v8, s33, v1
	v_lshl_add_u64 v[158:159], v[2:3], 0, s[6:7]
	v_lshrrev_b32_e32 v3, 3, v1
	v_and_b32_e32 v4, 48, v1
	v_mov_b32_e32 v5, v0
	v_lshrrev_b32_e32 v236, 6, v8
	v_and_b32_e32 v237, 7, v1
	v_and_b32_e32 v238, 15, v1
	v_lshl_or_b32 v160, v236, 3, v237
	v_mul_u32_u24_e32 v243, 0xc00, v236
	v_lshlrev_b32_e32 v244, 4, v1
	v_lshrrev_b32_e32 v239, 4, v160
	v_and_b32_e32 v240, 15, v160
	v_lshlrev_b32_e32 v241, 11, v239
	v_mul_u32_u24_e32 v239, 0xc00, v239
	v_lshlrev_b32_e32 v240, 4, v240
	v_lshl_add_u32 v239, v3, 8, v239
	v_bfe_u32 v242, v3, 2, 1
	v_add_u32_e32 v239, v239, v240
	v_lshl_or_b32 v241, v242, 10, v241
	v_and_b32_e32 v242, 1, v3
	v_or_b32_e32 v241, v241, v240
	v_lshl_or_b32 v241, v242, 9, v241
	v_bfe_u32 v242, v3, 1, 1
	v_add_u32_e32 v243, v243, v244
	v_lshl_or_b32 v241, v242, 3, v241
	v_add_u32_e32 v243, 0x800, v243
	v_lshl_add_u64 v[6:7], s[14:15], 0, v[4:5]
	s_mov_b64 s[6:7], 0x208c0000
	v_lshlrev_b32_e32 v166, 4, v3
	s_movk_i32 s21, 0xd0
	v_lshl_add_u64 v[164:165], v[6:7], 0, s[6:7]
	s_movk_i32 s6, 0x90
	v_lshlrev_b32_e32 v2, 3, v3
	s_movk_i32 s6, 0x100
	v_cmp_gt_i32_e64 s[10:11], s6, v8
	s_movk_i32 s6, 0xff
	s_add_u32 s30, s8, 0x2ccc0000
	v_lshl_or_b32 v162, v236, 4, v238
	v_and_b32_e32 v162, 63, v162
	v_cmp_lt_i32_e64 s[12:13], s6, v8
	v_lshlrev_b32_e32 v8, 2, v9
	s_addc_u32 s31, s9, 0
	v_ashrrev_i32_e32 v9, 31, v8
	s_load_dword s68, s[0:1], 0x108
	s_add_u32 s34, s28, 0x338c0000
	v_and_b32_e32 v156, 15, v1
	v_lshl_add_u64 v[8:9], v[8:9], 1, s[16:17]
	s_mov_b64 s[6:7], 0x3b8c0000
	v_lshl_or_b32 v4, v162, 6, v4
	v_mov_b32_e32 v5, v0
	s_addc_u32 s35, s29, 0
	s_ashr_i32 s33, s18, 31
	v_ashrrev_i32_e32 v161, 31, v160
	v_lshl_add_u64 v[168:169], v[8:9], 0, s[6:7]
	v_lshl_add_u64 v[4:5], s[14:15], 0, v[4:5]
	s_mov_b64 s[6:7], 0x208c6000
	s_mov_b32 s73, s5
	s_cmpk_gt_u32 s5, 0xff
	v_lshl_add_u64 v[170:171], v[4:5], 0, s[6:7]
	v_lshlrev_b64 v[4:5], 10, v[160:161]
	s_mov_b32 s69, s4
	v_readlane_b32 s4, v255, 12
	v_readlane_b32 s70, v255, 4
	v_readlane_b32 s54, v255, 6
	s_mov_b32 s64, s18
	s_mov_b32 s37, 0
	s_cselect_b64 s[38:39], -1, 0
	v_mov_b32_e32 v167, v0
	v_lshl_add_u64 v[172:173], s[8:9], 0, v[4:5]
	v_mov_b64_e32 v[174:175], 0x7ff
	s_movk_i32 s6, 0x600
	s_mov_b64 s[40:41], 0x6000
	s_movk_i32 s7, 0x6000
	v_lshlrev_b32_e32 v176, 1, v2
	s_mov_b32 s8, 0x40c00000
	s_mov_b32 s52, 0x2cd10000
	s_mov_b32 s53, 0
	s_mov_b32 s56, 0x338c0000
	s_mov_b32 s57, 0
	s_mov_b32 s58, 0x2cd20000
	s_mov_b32 s59, 0
	s_mov_b64 s[42:43], 0x100
	s_mov_b64 s[44:45], 0x2000
	s_mov_b64 s[46:47], 0x20000
	v_mov_b32_e32 v196, 0x600
	v_mov_b32_e32 v197, v239
	v_mov_b32_e32 v198, v241
	v_mov_b32_e32 v199, v243
	v_mov_b32_e32 v200, v244
	s_mov_b32 s9, s2
	s_mov_b32 s21, 0
	v_readlane_b32 s5, v255, 13
	v_readlane_b32 s71, v255, 5
	v_readlane_b32 s55, v255, 7
	s_branch .LBB0_859

.LBB0_887:
	v_lshl_add_u64 v[186:187], v[182:183], 0, v[166:167]
	v_lshl_add_u64 v[32:33], v[186:187], 0, s[52:53]
	global_load_dwordx4 v[32:35], v[32:33], off
	s_and_saveexec_b64 s[14:15], s[10:11]
	s_cbranch_execz .LBB0_890
	global_load_dwordx4 v[36:39], v[180:181], off offset:-4096

.LBB0_891:
	v_lshl_add_u64 v[188:189], v[2:3], 0, v[166:167]
	v_lshl_add_u64 v[40:41], v[188:189], 0, s[56:57]
	global_load_dwordx4 v[40:43], v[40:41], off offset:512

.LBB0_895:
	ds_read_b128 v[124:127], v201 offset:12288
	ds_read_b128 v[128:131], v201 offset:13312
	ds_read_b128 v[136:139], v201 offset:15360
	ds_read_b128 v[140:143], v201 offset:14336
	ds_read_b128 v[148:151], v201 offset:18432
	ds_read_b128 v[152:155], v201 offset:19456
	ds_read_b128 v[204:207], v201 offset:21504
	ds_read_b128 v[208:211], v201 offset:20480
	s_waitcnt lgkmcnt(7)
	v_mfma_f32_16x16x32_bf16 v[132:135], v[124:127], v[12:15], v[44:47]
	v_exp_f32_e32 v195, v84
	v_exp_f32_e32 v194, v88
	v_exp_f32_e32 v88, v91
	v_mfma_f32_16x16x32_bf16 v[124:127], v[124:127], v[16:19], v[48:51]
	v_exp_f32_e32 v84, v81
	v_exp_f32_e32 v81, v78
	v_exp_f32_e32 v79, v79
	s_waitcnt lgkmcnt(3)
	v_mfma_f32_16x16x32_bf16 v[190:193], v[148:151], v[12:15], v[44:47]
	v_exp_f32_e32 v78, v83
	v_exp_f32_e32 v61, v61
	v_exp_f32_e32 v63, v63
	v_mfma_f32_16x16x32_bf16 v[148:151], v[148:151], v[16:19], v[48:51]
	v_exp_f32_e32 v83, v64
	v_exp_f32_e32 v64, v74
	v_exp_f32_e32 v67, v67
	v_mfma_f32_16x16x32_bf16 v[144:147], v[136:139], v[12:15], v[44:47]
	v_mfma_f32_16x16x32_bf16 v[136:139], v[136:139], v[16:19], v[48:51]
	s_waitcnt lgkmcnt(1)
	v_mfma_f32_16x16x32_bf16 v[212:215], v[204:207], v[12:15], v[44:47]
	v_mfma_f32_16x16x32_bf16 v[204:207], v[204:207], v[16:19], v[48:51]
	v_mfma_f32_16x16x32_bf16 v[132:135], v[128:131], v[4:7], v[132:135]
	v_mfma_f32_16x16x32_bf16 v[124:127], v[128:131], v[20:23], v[124:127]
	ds_read_b128 v[128:131], v201 offset:16384
	ds_read_b128 v[216:219], v201 offset:17408
	v_mfma_f32_16x16x32_bf16 v[220:223], v[152:155], v[20:23], v[148:151]
	s_nop 2
	ds_read_b128 v[148:151], v201 offset:22528
	ds_read_b128 v[224:227], v201 offset:23552
	s_waitcnt lgkmcnt(3)
	v_mfma_f32_16x16x32_bf16 v[144:147], v[128:131], v[4:7], v[144:147]
	v_mfma_f32_16x16x32_bf16 v[128:131], v[128:131], v[20:23], v[136:139]
	s_waitcnt lgkmcnt(1)
	v_mfma_f32_16x16x32_bf16 v[204:207], v[148:151], v[20:23], v[204:207]
	v_mfma_f32_16x16x32_bf16 v[136:139], v[152:155], v[4:7], v[190:193]
	v_mfma_f32_16x16x32_bf16 v[212:215], v[148:151], v[4:7], v[212:215]
	s_nop 1
	v_exp_f32_e32 v193, v85
	v_exp_f32_e32 v192, v89
	v_exp_f32_e32 v191, v86
	v_mfma_f32_16x16x32_bf16 v[148:151], v[140:143], v[8:11], v[132:135]
	v_exp_f32_e32 v190, v90
	v_exp_f32_e32 v89, v87
	v_exp_f32_e32 v87, v76
	v_mfma_f32_16x16x32_bf16 v[152:155], v[140:143], v[24:27], v[124:127]
	v_exp_f32_e32 v86, v80
	v_exp_f32_e32 v85, v77
	v_exp_f32_e32 v80, v82
	v_mfma_f32_16x16x32_bf16 v[140:143], v[216:219], v[8:11], v[144:147]
	v_exp_f32_e32 v77, v60
	v_exp_f32_e32 v76, v68
	v_exp_f32_e32 v60, v69
	v_mfma_f32_16x16x32_bf16 v[144:147], v[216:219], v[24:27], v[128:131]
	v_exp_f32_e32 v69, v62
	v_exp_f32_e32 v68, v70
	v_exp_f32_e32 v62, v71
	s_waitcnt lgkmcnt(0)
	v_mfma_f32_16x16x32_bf16 v[128:131], v[224:227], v[24:27], v[204:207]
	v_exp_f32_e32 v82, v72
	v_exp_f32_e32 v71, v65
	v_exp_f32_e32 v70, v73
	ds_read_b128 v[204:207], v200 offset:24576
	v_mfma_f32_16x16x32_bf16 v[132:135], v[208:211], v[8:11], v[136:139]
	v_exp_f32_e32 v65, v66
	v_exp_f32_e32 v66, v75
	v_cvt_pk_bf16_f32 v90, v77, v61
	v_mfma_f32_16x16x32_bf16 v[136:139], v[208:211], v[24:27], v[220:223]
	v_cvt_pk_bf16_f32 v208, v195, v193
	v_cvt_pk_bf16_f32 v209, v191, v89
	v_cvt_pk_bf16_f32 v210, v87, v85
	v_mfma_f32_16x16x32_bf16 v[124:127], v[224:227], v[8:11], v[212:215]
	v_cvt_pk_bf16_f32 v211, v81, v79
	ds_read_b128 v[216:219], v200 offset:26624
	ds_read_b128 v[220:223], v200 offset:25600
	v_cvt_pk_bf16_f32 v212, v194, v192
	v_cvt_pk_bf16_f32 v213, v190, v88
	v_cvt_pk_bf16_f32 v214, v86, v84
	v_cvt_pk_bf16_f32 v215, v80, v78
	s_waitcnt lgkmcnt(2)
	v_mfma_f32_16x16x32_bf16 v[120:123], v[204:207], v[208:211], v[120:123]
	v_cvt_pk_bf16_f32 v91, v69, v63
	v_mfma_f32_16x16x32_bf16 v[104:107], v[204:207], v[212:215], v[104:107]
	ds_read_b128 v[204:207], v200 offset:28672
	ds_read_b128 v[224:227], v200 offset:27648
	s_waitcnt lgkmcnt(3)
	v_mfma_f32_16x16x32_bf16 v[228:231], v[216:219], v[208:211], v[116:119]
	v_mfma_f32_16x16x32_bf16 v[100:103], v[216:219], v[212:215], v[100:103]
	s_nop 1
	ds_read_b128 v[116:119], v200 offset:30720
	ds_read_b128 v[216:219], v200 offset:29696
	s_waitcnt lgkmcnt(3)
	v_mfma_f32_16x16x32_bf16 v[232:235], v[204:207], v[208:211], v[112:115]
	v_mfma_f32_16x16x32_bf16 v[96:99], v[204:207], v[212:215], v[96:99]
	ds_read_b128 v[204:207], v200 offset:31744
	s_waitcnt lgkmcnt(2)
	v_mfma_f32_16x16x32_bf16 v[208:211], v[116:119], v[208:211], v[108:111]
	v_mfma_f32_16x16x32_bf16 v[72:75], v[116:119], v[212:215], v[92:95]
	v_cvt_pk_bf16_f32 v212, v76, v60
	v_cvt_pk_bf16_f32 v213, v68, v62
	v_cvt_pk_bf16_f32 v214, v82, v70
	v_cvt_pk_bf16_f32 v92, v83, v71
	v_cvt_pk_bf16_f32 v93, v65, v67
	v_cvt_pk_bf16_f32 v215, v64, v66
	s_nop 0
	v_mfma_f32_16x16x32_bf16 v[120:123], v[220:223], v[90:93], v[120:123]
	v_mfma_f32_16x16x32_bf16 v[116:119], v[220:223], v[212:215], v[104:107]
	v_max3_f32 v244, v152, v153, v154
	v_max3_f32 v245, v148, v149, v150
	v_mfma_f32_16x16x32_bf16 v[112:115], v[224:227], v[90:93], v[228:231]
	v_max3_f32 v244, v244, v155, v144
	v_max3_f32 v245, v245, v151, v140
	v_mfma_f32_16x16x32_bf16 v[108:111], v[224:227], v[212:215], v[100:103]
	v_max3_f32 v244, v244, v145, v146
	v_max3_f32 v245, v245, v141, v142
	s_waitcnt lgkmcnt(1)
	v_mfma_f32_16x16x32_bf16 v[104:107], v[216:219], v[90:93], v[232:235]
	v_max3_f32 v244, v244, v147, v136
	v_max3_f32 v245, v245, v143, v132
	v_mfma_f32_16x16x32_bf16 v[100:103], v[216:219], v[212:215], v[96:99]
	v_max3_f32 v244, v244, v137, v138
	v_max3_f32 v245, v245, v133, v134
	s_waitcnt lgkmcnt(0)
	v_mfma_f32_16x16x32_bf16 v[92:95], v[204:207], v[90:93], v[208:211]
	v_max3_f32 v244, v244, v139, v128
	v_max3_f32 v245, v245, v135, v124
	v_mfma_f32_16x16x32_bf16 v[96:99], v[204:207], v[212:215], v[72:75]
	v_max3_f32 v244, v244, v129, v130
	v_max3_f32 v245, v245, v125, v126
	s_waitcnt vmcnt(0)
	ds_write_b128 v197, v[52:55]
	s_and_saveexec_b64 s[16:17], s[10:11]
	ds_write_b128 v199, v[28:31]
	s_or_b64 exec, exec, s[16:17]
.LBB0_899:
	ds_write2_b64 v1, v[56:57], v[58:59] offset1:32
	s_waitcnt lgkmcnt(0)
	s_barrier
	v_lshl_add_u64 v[52:53], v[186:187], 0, s[58:59]
	global_load_dwordx4 v[52:55], v[52:53], off
	s_and_saveexec_b64 s[16:17], s[10:11]
	s_cbranch_execz .LBB0_902
	global_load_dwordx4 v[28:31], v[180:181], off

.LBB0_903:
	v_lshl_add_u64 v[56:57], v[188:189], 0, s[56:57]
	global_load_dwordx4 v[56:59], v[56:57], off offset:640

.LBB0_907:
	ds_read_b128 v[60:63], v201
	ds_read_b128 v[64:67], v201 offset:1024
	ds_read_b128 v[72:75], v201 offset:3072
	ds_read_b128 v[76:79], v201 offset:2048
	ds_read_b128 v[84:87], v201 offset:6144
	ds_read_b128 v[88:91], v201 offset:7168
	ds_read_b128 v[190:193], v201 offset:9216
	ds_read_b128 v[204:207], v201 offset:8192
	s_waitcnt lgkmcnt(7)
	v_mfma_f32_16x16x32_bf16 v[68:71], v[60:63], v[12:15], v[44:47]
	v_exp_f32_e32 v149, v149
	v_exp_f32_e32 v151, v151
	v_exp_f32_e32 v143, v143
	v_mfma_f32_16x16x32_bf16 v[60:63], v[60:63], v[16:19], v[48:51]
	v_exp_f32_e32 v133, v133
	v_exp_f32_e32 v135, v135
	v_exp_f32_e32 v127, v127
	s_waitcnt lgkmcnt(3)
	v_mfma_f32_16x16x32_bf16 v[186:189], v[84:87], v[12:15], v[44:47]
	v_mfma_f32_16x16x32_bf16 v[84:87], v[84:87], v[16:19], v[48:51]
	v_mfma_f32_16x16x32_bf16 v[80:83], v[72:75], v[12:15], v[44:47]
	v_mfma_f32_16x16x32_bf16 v[72:75], v[72:75], v[16:19], v[48:51]
	s_waitcnt lgkmcnt(1)
	v_mfma_f32_16x16x32_bf16 v[208:211], v[190:193], v[12:15], v[44:47]
	v_mfma_f32_16x16x32_bf16 v[190:193], v[190:193], v[16:19], v[48:51]
	v_mfma_f32_16x16x32_bf16 v[68:71], v[64:67], v[4:7], v[68:71]
	v_mfma_f32_16x16x32_bf16 v[60:63], v[64:67], v[20:23], v[60:63]
	ds_read_b128 v[64:67], v201 offset:4096
	ds_read_b128 v[212:215], v201 offset:5120
	v_mfma_f32_16x16x32_bf16 v[216:219], v[88:91], v[20:23], v[84:87]
	s_nop 2
	ds_read_b128 v[84:87], v201 offset:10240
	ds_read_b128 v[220:223], v201 offset:11264
	s_waitcnt lgkmcnt(3)
	v_mfma_f32_16x16x32_bf16 v[80:83], v[64:67], v[4:7], v[80:83]
	v_mfma_f32_16x16x32_bf16 v[64:67], v[64:67], v[20:23], v[72:75]
	v_mfma_f32_16x16x32_bf16 v[72:75], v[88:91], v[4:7], v[186:189]
	s_waitcnt lgkmcnt(1)
	v_mfma_f32_16x16x32_bf16 v[188:191], v[84:87], v[20:23], v[190:193]
	s_nop 0
	v_exp_f32_e32 v187, v148
	v_exp_f32_e32 v186, v152
	v_exp_f32_e32 v148, v153
	v_mfma_f32_16x16x32_bf16 v[88:91], v[76:79], v[24:27], v[60:63]
	v_exp_f32_e32 v153, v150
	v_exp_f32_e32 v152, v154
	v_exp_f32_e32 v150, v155
	v_mfma_f32_16x16x32_bf16 v[60:63], v[204:207], v[8:11], v[72:75]
	v_exp_f32_e32 v155, v141
	v_exp_f32_e32 v154, v145
	v_exp_f32_e32 v145, v142
	s_waitcnt lgkmcnt(0)
	v_mfma_f32_16x16x32_bf16 v[72:75], v[220:223], v[24:27], v[188:191]
	v_exp_f32_e32 v142, v147
	v_exp_f32_e32 v141, v132
	v_exp_f32_e32 v132, v137
	ds_read_b128 v[190:193], v200 offset:32768
	v_mfma_f32_16x16x32_bf16 v[208:211], v[84:87], v[4:7], v[208:211]
	v_exp_f32_e32 v189, v140
	v_exp_f32_e32 v188, v144
	v_exp_f32_e32 v144, v146
	v_mfma_f32_16x16x32_bf16 v[84:87], v[76:79], v[8:11], v[68:71]
	v_exp_f32_e32 v140, v136
	v_exp_f32_e32 v137, v134
	v_exp_f32_e32 v136, v138
	v_mfma_f32_16x16x32_bf16 v[76:79], v[212:215], v[8:11], v[80:83]
	v_exp_f32_e32 v134, v139
	v_exp_f32_e32 v139, v124
	v_exp_f32_e32 v138, v128
	v_mfma_f32_16x16x32_bf16 v[80:83], v[212:215], v[24:27], v[64:67]
	v_exp_f32_e32 v147, v125
	v_exp_f32_e32 v146, v129
	v_exp_f32_e32 v125, v126
	v_mfma_f32_16x16x32_bf16 v[68:71], v[204:207], v[24:27], v[216:219]
	ds_read_b128 v[212:215], v200 offset:34816
	s_nop 1
	ds_read_b128 v[216:219], v200 offset:33792
	v_cvt_pk_bf16_f32 v204, v187, v149
	v_cvt_pk_bf16_f32 v205, v153, v151
	v_mfma_f32_16x16x32_bf16 v[64:67], v[220:223], v[8:11], v[208:211]
	v_cvt_pk_bf16_f32 v206, v189, v155
	v_cvt_pk_bf16_f32 v207, v145, v143
	v_exp_f32_e32 v124, v130
	v_cvt_pk_bf16_f32 v208, v186, v148
	v_cvt_pk_bf16_f32 v209, v152, v150
	v_cvt_pk_bf16_f32 v210, v188, v154
	v_cvt_pk_bf16_f32 v211, v144, v142
	s_waitcnt lgkmcnt(2)
	v_mfma_f32_16x16x32_bf16 v[120:123], v[190:193], v[204:207], v[120:123]
	v_exp_f32_e32 v126, v131
	v_mfma_f32_16x16x32_bf16 v[116:119], v[190:193], v[208:211], v[116:119]
	ds_read_b128 v[190:193], v200 offset:36864
	ds_read_b128 v[220:223], v200 offset:35840
	s_waitcnt lgkmcnt(3)
	v_mfma_f32_16x16x32_bf16 v[112:115], v[212:215], v[204:207], v[112:115]
	v_mfma_f32_16x16x32_bf16 v[108:111], v[212:215], v[208:211], v[108:111]
	ds_read_b128 v[212:215], v200 offset:38912
	ds_read_b128 v[224:227], v200 offset:37888
	ds_read_b128 v[232:235], v200 offset:39936
	s_waitcnt lgkmcnt(4)
	v_mfma_f32_16x16x32_bf16 v[228:231], v[190:193], v[204:207], v[104:107]
	v_mfma_f32_16x16x32_bf16 v[190:193], v[190:193], v[208:211], v[100:103]
	s_waitcnt lgkmcnt(2)
	v_mfma_f32_16x16x32_bf16 v[92:95], v[212:215], v[204:207], v[92:95]
	v_cvt_pk_bf16_f32 v204, v141, v133
	v_cvt_pk_bf16_f32 v205, v137, v135
	v_cvt_pk_bf16_f32 v206, v139, v147
	v_mfma_f32_16x16x32_bf16 v[128:131], v[212:215], v[208:211], v[96:99]
	v_cvt_pk_bf16_f32 v207, v125, v127
	v_cvt_pk_bf16_f32 v208, v140, v132
	v_cvt_pk_bf16_f32 v209, v136, v134
	v_cvt_pk_bf16_f32 v210, v138, v146
	v_cvt_pk_bf16_f32 v211, v124, v126
	v_mfma_f32_16x16x32_bf16 v[120:123], v[216:219], v[204:207], v[120:123]
	s_nop 0
	v_mfma_f32_16x16x32_bf16 v[104:107], v[216:219], v[208:211], v[116:119]
	v_max3_f32 v246, v88, v89, v90
	v_max3_f32 v247, v84, v85, v86
	v_mfma_f32_16x16x32_bf16 v[116:119], v[220:223], v[204:207], v[112:115]
	v_max3_f32 v246, v246, v91, v80
	v_max3_f32 v247, v247, v87, v76
	v_mfma_f32_16x16x32_bf16 v[100:103], v[220:223], v[208:211], v[108:111]
	v_max3_f32 v246, v246, v81, v82
	v_max3_f32 v247, v247, v77, v78
	s_waitcnt lgkmcnt(1)
	v_mfma_f32_16x16x32_bf16 v[112:115], v[224:227], v[204:207], v[228:231]
	v_max3_f32 v246, v246, v83, v68
	v_max3_f32 v247, v247, v79, v60
	v_mfma_f32_16x16x32_bf16 v[96:99], v[224:227], v[208:211], v[190:193]
	v_max3_f32 v246, v246, v69, v70
	v_max3_f32 v247, v247, v61, v62
	s_waitcnt lgkmcnt(0)
	v_mfma_f32_16x16x32_bf16 v[108:111], v[232:235], v[204:207], v[92:95]
	v_max3_f32 v246, v246, v71, v72
	v_max3_f32 v247, v247, v63, v64
	v_mfma_f32_16x16x32_bf16 v[92:95], v[232:235], v[208:211], v[128:131]
	v_max3_f32 v246, v246, v73, v74
	v_max3_f32 v247, v247, v65, v66
	ds_write_b128 v197, v[32:35] offset:12288
	s_and_saveexec_b64 s[16:17], s[10:11]
	ds_write_b128 v199, v[36:39] offset:12288
	s_or_b64 exec, exec, s[16:17]
; DI void attn_phase(LAS unsigned char* lds, const int wid, const bf16_t* Q, const bf16_t* Kn, const bf16_t* Kr, const bf16_t* Vt, bf16_t* O, int G, int c) {
;     ...
;         for (int kt = 0; kt < NKT; kt += 2) {
;             ATT_STEP(kt, bkn, bkr, bvt, akn, akr, avt, sa, sb);
;             ATT_STEP(kt + 1, akn, akr, avt, bkn, bkr, bvt, sb, sa);
;         }
.LBB0_911:
	ds_write2_b64 v177, v[40:41], v[42:43] offset1:32
	v_pk_add_f32 v[236:237], v[186:187], v[188:189]
	v_pk_add_f32 v[238:239], v[148:149], v[154:155]
	v_pk_add_f32 v[240:241], v[144:145], v[152:153]
	v_pk_add_f32 v[242:243], v[142:143], v[150:151]
	v_pk_add_f32 v[236:237], v[236:237], v[140:141]
	v_pk_add_f32 v[238:239], v[238:239], v[132:133]
	v_pk_add_f32 v[240:241], v[136:137], v[240:241]
	v_pk_add_f32 v[242:243], v[134:135], v[242:243]
	v_pk_add_f32 v[236:237], v[236:237], v[138:139]
	v_pk_add_f32 v[238:239], v[238:239], v[146:147]
	v_pk_add_f32 v[240:241], v[124:125], v[240:241]
	v_pk_add_f32 v[242:243], v[126:127], v[242:243]
	s_add_i32 s26, s26, 2
	v_pk_add_f32 v[240:241], v[240:241], v[242:243]
	v_pk_add_f32 v[236:237], v[236:237], v[238:239]
	v_lshl_add_u64 v[2:3], v[2:3], 0, s[42:43]
	v_pk_add_f32 v[236:237], v[236:237], v[240:241]
	v_lshl_add_u64 v[180:181], v[180:181], 0, s[44:45]
	v_pk_add_f32 v[184:185], v[184:185], v[236:237]
	v_lshl_add_u64 v[182:183], v[182:183], 0, s[46:47]
	s_cmpk_gt_u32 s26, 0x7f
	s_waitcnt lgkmcnt(0)
	s_barrier
	s_cbranch_scc0 .LBB0_887
	s_waitcnt vmcnt(0)
	s_branch .LBB0_857
